# attention: waves 4-7 take the per-half-step workgroup barrier right after their PV MFMAs (next-K slice written first) and run partialSM after it; waves 0-3 unchanged -> the two waves of a SIMD run hal
# baseline (speedup 1.0000x reference)
; __device__ __forceinline__ int opaque_tid() { int t = threadIdx.x; asm volatile("" : "+v"(t)); return t; }
; __device__ __forceinline__ u32x4 pack8(f32x4 a, f32x4 b) { u32x4 w; w.x = cvt_pk_bf16(a[0], a[1]); w.y = cvt_pk_bf16(a[2], a[3]); w.z = cvt_pk_bf16(b[0], b[1]); w.w = cvt_pk_bf16(b[2], b[3]); return w; }
; __device__ __forceinline__ bf16x8 pack8(f32x4 a, f32x4 b) { u32x4 w = {cvtpk(a[0], a[1]), cvtpk(a[2], a[3]), cvtpk(b[0], b[1]), cvtpk(b[2], b[3])}; return *reinterpret_cast<bf16x8*>(&w); }
; #define VMW() asm volatile("s_waitcnt vmcnt(0)" ::: "memory")
; #define SLOAD_H(Kp, Vp, k0) do { S.st_v0 = load8(ROW(Vp, k0, sr)); S.st_v1 = load8(ROW(Vp, k0, 32 + sr));              \
;                          S.st_k0 = load8(ROW(Kp, k0, sr)); S.st_k1 = load8(ROW(Kp, k0, 32 + sr)); } while (0)
; #define SWRITE_HK(bf) do { *(bf16x8*)(K_lds + (bf) * SHM_K + kws) = S.st_k0; *(bf16x8*)(K_lds + (bf) * SHM_K + kws + 32 * 256) = S.st_k1; } while (0)
; __device__ __forceinline__ void stage_kmean(char* lds, const float* km) {
;     const int tid = opaque_tid(), row = tid >> 4, chunk = tid & 15;
;     const float* kp = km + (row & 15) * 128 + chunk * 8;
;     f32x4 a = *(const f32x4*)kp, b = *(const f32x4*)(kp + 4);
;     a = a * (1.0f / 256.0f); b = b * (1.0f / 256.0f);
;     const bf16x8 h = pack8(a, b);
;     f32x4 ah, bh;
; #pragma unroll
;     for (int j = 0; j < 4; ++j) { ah[j] = __uint_as_float(((unsigned)(unsigned short)h[j]) << 16); bh[j] = __uint_as_float(((unsigned)(unsigned short)h[4 + j]) << 16); }
;     const bf16x8 l = pack8(a - ah, b - bh);
;     *(bf16x8*)(lds + KM_LDS_OFF + row * KM_PITCH + chunk * 16) = (row >= 16) ? l : h;
; }
; __device__ __forceinline__ void moba_prime(const BlockRef& cur, char* lds, Seam& S) {
;     const int tid = opaque_tid(), wid = __builtin_amdgcn_readfirstlane(tid >> 6), lane = tid & 63, r32 = lane & 31, hi = lane >> 5;
;     const int sr = tid >> 4, sc = (tid & 15) * 8, kws = KSWZ(sr, sc * 2); char* K_lds = lds + 2 * SHM_V;
;     for (int d0 = 0; d0 < 8; ++d0) S.qr[d0] = load8(cur.Q + (size_t)(wid * QBLK + r32) * D + d0 * 16 + hi * 8);
;     SLOAD_H(cur.K, cur.V, 0); VMW(); SWRITE_HK(0);
;     __syncthreads();
; }
.LBB0_75:
.LBB0_76:
	v_readlane_b32 s0, v254, 4
	v_readlane_b32 s1, v254, 5
	s_andn2_b64 vcc, exec, s[0:1]
	s_cbranch_vccnz .LBB0_247
	v_readfirstlane_b32 s32, v0
	s_lshr_b32 s32, s32, 8
	s_and_b64 s[0:1], s[72:73], exec
	s_cselect_b32 s0, 0x40000, 0
	v_readlane_b32 s2, v253, 37
	v_readlane_b32 s3, v253, 38
	s_add_u32 s45, s2, s0
	s_waitcnt vmcnt(0)
	v_mov_b32_e32 v2, v0
	s_addc_u32 s79, s3, 0
	v_readlane_b32 s0, v254, 0
	v_readlane_b32 s1, v254, 1
	v_ashrrev_i32_e32 v18, 4, v2
	s_add_u32 s18, s45, s0
	v_and_b32_e32 v19, 15, v2
	v_lshlrev_b32_e32 v2, 9, v18
	s_addc_u32 s19, s79, s1
	v_and_b32_e32 v98, 0x1e00, v2
	s_waitcnt lgkmcnt(0)
	v_lshl_add_u64 v[2:3], s[18:19], 0, v[98:99]
	v_lshlrev_b32_e32 v98, 5, v19
	v_lshl_add_u64 v[6:7], v[2:3], 0, v[98:99]
	global_load_dwordx4 v[2:5], v[6:7], off offset:16
	s_nop 0
	global_load_dwordx4 v[6:9], v[6:7], off
	s_mov_b32 s0, 0x3b800000
	v_cmp_lt_i32_e32 vcc, 15, v18
	v_readlane_b32 s14, v253, 49
	v_readlane_b32 s15, v253, 50
	v_readlane_b32 s22, v253, 57
	v_readlane_b32 s23, v253, 58
	v_readlane_b32 s30, v253, 53
	v_readlane_b32 s31, v253, 54
	s_mov_b64 s[46:47], s[92:93]
	v_readlane_b32 s92, v253, 62
	v_readlane_b32 s44, v253, 59
	v_readlane_b32 s2, v253, 48
	v_readlane_b32 s93, v253, 63
	s_mov_b64 s[10:11], -1
	s_mov_b32 s85, s90
	s_mov_b32 s86, s44
	s_mov_b32 s89, s2
	s_mov_b64 s[4:5], s[92:93]
	s_mov_b64 s[16:17], s[22:23]
	s_mov_b64 s[28:29], s[30:31]
	s_waitcnt vmcnt(1)
	v_pk_mul_f32 v[14:15], v[4:5], s[0:1] op_sel_hi:[1,0]
	s_waitcnt vmcnt(0)
	v_pk_mul_f32 v[10:11], v[8:9], s[0:1] op_sel_hi:[1,0]
	s_waitcnt lgkmcnt(0)
	v_pk_mul_f32 v[12:13], v[6:7], s[0:1] op_sel_hi:[1,0]
	v_pk_mul_f32 v[16:17], v[2:3], s[0:1] op_sel_hi:[1,0]
	v_cvt_pk_bf16_f32 v12, v12, v13
	v_cvt_pk_bf16_f32 v13, v10, v11
	s_nop 0
	v_lshlrev_b32_e32 v10, 16, v13
	v_and_b32_e32 v11, 0xffff0000, v13
	v_lshlrev_b32_e32 v21, 16, v12
	v_and_b32_e32 v22, 0xffff0000, v12
	v_xor_b32_e32 v11, 0x80000000, v11
	v_xor_b32_e32 v10, 0x80000000, v10
	v_cvt_pk_bf16_f32 v16, v16, v17
	v_cvt_pk_bf16_f32 v14, v14, v15
	v_pk_fma_f32 v[8:9], v[8:9], s[0:1], v[10:11] op_sel_hi:[1,0,1]
	v_lshlrev_b32_e32 v20, 16, v14
	v_and_b32_e32 v23, 0xffff0000, v14
	v_xor_b32_e32 v11, 0x80000000, v22
	v_xor_b32_e32 v10, 0x80000000, v21
	v_lshlrev_b32_e32 v15, 16, v16
	v_and_b32_e32 v17, 0xffff0000, v16
	v_pk_fma_f32 v[6:7], v[6:7], s[0:1], v[10:11] op_sel_hi:[1,0,1]
	v_xor_b32_e32 v11, 0x80000000, v23
	v_xor_b32_e32 v10, 0x80000000, v20
	v_pk_fma_f32 v[4:5], v[4:5], s[0:1], v[10:11] op_sel_hi:[1,0,1]
	v_xor_b32_e32 v11, 0x80000000, v17
	v_xor_b32_e32 v10, 0x80000000, v15
	v_pk_fma_f32 v[2:3], v[2:3], s[0:1], v[10:11] op_sel_hi:[1,0,1]
	v_cvt_pk_bf16_f32 v6, v6, v7
	v_cvt_pk_bf16_f32 v7, v8, v9
	s_movk_i32 s0, 0x110
	v_cvt_pk_bf16_f32 v8, v2, v3
	v_cvt_pk_bf16_f32 v2, v4, v5
	v_cndmask_b32_e32 v3, v13, v7, vcc
	v_cndmask_b32_e32 v5, v14, v2, vcc
	v_cndmask_b32_e32 v2, v12, v6, vcc
	v_mul_lo_u32 v6, v18, s0
	v_lshlrev_b32_e32 v7, 4, v19
	v_readlane_b32 s0, v255, 35
	v_cndmask_b32_e32 v4, v16, v8, vcc
	s_nop 0
	v_add3_u32 v6, s0, v6, v7
	ds_write_b128 v6, v[2:5]
	v_mov_b32_e32 v4, v0
	s_nop 0
	v_readfirstlane_b32 s0, v4
	s_ashr_i32 s0, s0, 1
	v_lshrrev_b32_e32 v5, 1, v4
	v_mov_b32_e32 v2, s0
	s_movk_i32 s0, 0xffe0
	v_bfi_b32 v2, s0, v2, v4
	v_ashrrev_i32_e32 v3, 31, v2
	v_lshlrev_b64 v[2:3], 8, v[2:3]
	v_lshl_add_u64 v[2:3], s[14:15], 0, v[2:3]
	v_and_b32_e32 v98, 16, v5
	v_lshl_add_u64 v[2:3], v[2:3], 0, v[98:99]
	global_load_dwordx4 v[132:135], v[2:3], off
	global_load_dwordx4 v[128:131], v[2:3], off offset:32
	global_load_dwordx4 v[124:127], v[2:3], off offset:64
	global_load_dwordx4 v[120:123], v[2:3], off offset:96
	global_load_dwordx4 v[116:119], v[2:3], off offset:128
	global_load_dwordx4 v[112:115], v[2:3], off offset:160
	global_load_dwordx4 v[108:111], v[2:3], off offset:192
	global_load_dwordx4 v[104:107], v[2:3], off offset:224
	v_ashrrev_i32_e32 v2, 4, v4
	v_lshlrev_b32_e32 v3, 4, v4
	v_and_b32_e32 v4, 0x70, v4
	s_movk_i32 s0, 0xf0
	v_and_b32_e32 v98, 0xf0, v3
	v_bitop3_b32 v11, v3, v4, s0 bitop3:0x6c
	v_ashrrev_i32_e32 v3, 31, v2
	v_lshlrev_b32_e32 v10, 8, v2
	v_lshlrev_b64 v[2:3], 8, v[2:3]
	v_lshl_add_u64 v[4:5], s[22:23], 0, v[2:3]
	s_mov_b64 s[0:1], 0x2000
	v_lshl_add_u64 v[4:5], v[4:5], 0, v[98:99]
	v_lshl_add_u64 v[6:7], v[2:3], 0, s[0:1]
	global_load_dwordx4 v[100:103], v[4:5], off
	v_lshl_add_u64 v[4:5], s[22:23], 0, v[6:7]
	v_lshl_add_u64 v[2:3], s[30:31], 0, v[2:3]
	v_lshl_add_u64 v[4:5], v[4:5], 0, v[98:99]
	v_lshl_add_u64 v[2:3], v[2:3], 0, v[98:99]
	v_lshl_add_u64 v[6:7], s[30:31], 0, v[6:7]
	global_load_dwordx4 v[136:139], v[4:5], off
	v_lshl_add_u64 v[6:7], v[6:7], 0, v[98:99]
	global_load_dwordx4 v[2:5], v[2:3], off
	v_add3_u32 v10, 0, v10, v11
	global_load_dwordx4 v[6:9], v[6:7], off
	s_waitcnt vmcnt(0)
	s_waitcnt vmcnt(1)
	ds_write_b128 v10, v[2:5] offset:32768
	s_waitcnt vmcnt(0)
	ds_write_b128 v10, v[6:9] offset:40960
	s_waitcnt lgkmcnt(0)
	s_barrier
	s_branch .LBB0_80

; __device__ __forceinline__ void finishSM(f32x16& p0, f32x16& p1, float alpha, float& l_reg, bf16x8& pa0, bf16x8& pa1, bf16x8& pa2, bf16x8& pa3) {
;     for (int r = 0; r < 16; ++r) p1[r] = __builtin_amdgcn_exp2f(p1[r]);
;     float ps = 0; for (int r = 0; r < 16; ++r) ps += p0[r]; for (int r = 0; r < 16; ++r) ps += p1[r];
;     { auto rr = __builtin_amdgcn_permlane32_swap(__float_as_uint(ps), __float_as_uint(ps), false, false);
;       ps = __uint_as_float(rr[0]) + __uint_as_float(rr[1]); }
;     l_reg = l_reg * alpha + ps;
;     ...
;     PK4(p0, 0, pa0); PK4(p0, 8, pa1); PK4(p1, 0, pa2); PK4(p1, 8, pa3);
;     ...
; }
; template <int KB>
; __device__ __forceinline__ void qkt(f32x16& p0, f32x16& p1, const char* K_lds, int r32, int hi, const bf16x8* qr) {
;     p0 = f32x16{}; p1 = f32x16{};
;     const char* kb[4];
; #pragma unroll
;     for (int dd = 0; dd < 4; ++dd) kb[dd] = K_lds + KB * SHM_K + KSWZ(r32, (dd * 16 + hi * 8) * 2);
; #pragma unroll
;     for (int d0 = 0; d0 < 8; ++d0) { const char* a = kb[d0 & 3] + (d0 >> 2) * 128;
;         bf16x8 b0 = *reinterpret_cast<const bf16x8*>(a);
;         bf16x8 b1 = *reinterpret_cast<const bf16x8*>(a + 32 * 256);
;         p0 = __builtin_amdgcn_mfma_f32_32x32x16_bf16(b0, qr[d0], p0, 0, 0, 0);
;         p1 = __builtin_amdgcn_mfma_f32_32x32x16_bf16(b1, qr[d0], p1, 0, 0, 0); }
.Lmy_hs1_nov:
	s_mov_b32 s100, 0
	ds_read_b128 v[66:69], v169 offset:49152
	ds_read_b128 v[70:73], v169 offset:57344
	ds_read_b128 v[100:103], v193 offset:49152
	ds_read_b128 v[136:139], v193 offset:57344
	v_add_f32_e32 v148, 0, v231
	v_add_f32_e32 v148, v233, v148
	v_add_f32_e32 v148, v229, v148
	v_add_f32_e32 v148, v232, v148
	v_add_f32_e32 v148, v228, v148
	v_add_f32_e32 v148, v230, v148
	v_add_f32_e32 v148, v226, v148
	v_add_f32_e32 v148, v227, v148
	v_add_f32_e32 v148, v223, v148
	v_add_f32_e32 v148, v225, v148
	v_add_f32_e32 v148, v209, v148
	v_add_f32_e32 v148, v224, v148
	v_add_f32_e32 v148, v206, v148
	v_add_f32_e32 v148, v208, v148
	v_add_f32_e32 v148, v205, v148
	v_add_f32_e32 v148, v207, v148
	v_exp_f32_e32 v140, v152
	v_exp_f32_e32 v141, v153
	v_exp_f32_e32 v142, v180
	v_exp_f32_e32 v143, v181
	s_waitcnt lgkmcnt(3)
	v_mfma_f32_32x32x16_bf16 v[82:97], v[66:69], v[132:135], 0
	v_exp_f32_e32 v144, v160
	v_exp_f32_e32 v145, v161
	v_exp_f32_e32 v146, v154
	v_exp_f32_e32 v147, v155
	s_waitcnt lgkmcnt(2)
	v_mfma_f32_32x32x16_bf16 v[66:81], v[70:73], v[132:135], 0
	v_exp_f32_e32 v178, v178
	v_exp_f32_e32 v179, v179
	v_exp_f32_e32 v162, v162
	v_exp_f32_e32 v163, v163
	s_waitcnt lgkmcnt(1)
	v_mfma_f32_32x32x16_bf16 v[82:97], v[100:103], v[128:131], v[82:97]
	v_add_f32_e32 v148, v178, v148
	v_add_f32_e32 v148, v179, v148
	v_add_f32_e32 v148, v162, v148
	v_exp_f32_e32 v158, v158
	s_waitcnt lgkmcnt(0)
	v_mfma_f32_32x32x16_bf16 v[66:81], v[136:139], v[128:131], v[66:81]
	v_exp_f32_e32 v159, v159
	v_exp_f32_e32 v156, v156
	v_exp_f32_e32 v157, v157
	v_add_f32_e32 v148, v163, v148
	ds_read_b128 v[100:103], v194 offset:49152
	ds_read_b128 v[136:139], v194 offset:57344
	s_waitcnt lgkmcnt(1)
	v_mfma_f32_32x32x16_bf16 v[82:97], v[100:103], v[124:127], v[82:97]
	v_add_f32_e32 v148, v158, v148
	v_add_f32_e32 v148, v159, v148
	v_add_f32_e32 v148, v156, v148
	v_add_f32_e32 v148, v157, v148
	s_waitcnt lgkmcnt(0)
	v_mfma_f32_32x32x16_bf16 v[66:81], v[136:139], v[124:127], v[66:81]
	v_add_f32_e32 v148, v140, v148
	v_add_f32_e32 v148, v141, v148
	v_add_f32_e32 v148, v142, v148
	v_add_f32_e32 v148, v143, v148
	ds_read_b128 v[100:103], v195 offset:49152
	ds_read_b128 v[136:139], v195 offset:57344
	s_waitcnt lgkmcnt(1)
	v_mfma_f32_32x32x16_bf16 v[82:97], v[100:103], v[120:123], v[82:97]
	v_add_f32_e32 v148, v144, v148
	v_add_f32_e32 v148, v145, v148
	v_add_f32_e32 v148, v146, v148
	v_add_f32_e32 v199, v147, v148
	s_waitcnt lgkmcnt(0)
	v_mfma_f32_32x32x16_bf16 v[66:81], v[136:139], v[120:123], v[66:81]
	v_mov_b32_e32 v200, v199
	s_nop 1
	v_permlane32_swap_b32_e32 v199, v200
	v_cvt_pk_bf16_f32 v148, v231, v233
	v_cvt_pk_bf16_f32 v149, v229, v232
	v_cvt_pk_bf16_f32 v150, v228, v230
	ds_read_b128 v[100:103], v169 offset:49280
	ds_read_b128 v[136:139], v169 offset:57472
	s_waitcnt lgkmcnt(1)
	v_mfma_f32_32x32x16_bf16 v[82:97], v[100:103], v[116:119], v[82:97]
	v_cvt_pk_bf16_f32 v151, v226, v227
	v_cvt_pk_bf16_f32 v152, v223, v225
	v_cvt_pk_bf16_f32 v153, v209, v224
	s_waitcnt lgkmcnt(0)
	v_mfma_f32_32x32x16_bf16 v[66:81], v[136:139], v[116:119], v[66:81]
	v_cvt_pk_bf16_f32 v154, v206, v208
	v_cvt_pk_bf16_f32 v155, v205, v207
	v_cvt_pk_bf16_f32 v158, v158, v159
	ds_read_b128 v[100:103], v193 offset:49280
	ds_read_b128 v[136:139], v193 offset:57472
	s_waitcnt lgkmcnt(1)
	v_mfma_f32_32x32x16_bf16 v[82:97], v[100:103], v[112:115], v[82:97]
	v_cvt_pk_bf16_f32 v159, v156, v157
	v_cvt_pk_bf16_f32 v156, v178, v179
	v_cvt_pk_bf16_f32 v157, v162, v163
	s_waitcnt lgkmcnt(0)
	v_mfma_f32_32x32x16_bf16 v[66:81], v[136:139], v[112:115], v[66:81]
	v_cvt_pk_bf16_f32 v160, v140, v141
	v_cvt_pk_bf16_f32 v161, v142, v143
	v_cvt_pk_bf16_f32 v162, v144, v145
	ds_read_b128 v[100:103], v194 offset:49280
	ds_read_b128 v[136:139], v194 offset:57472
	s_waitcnt lgkmcnt(1)
	v_mfma_f32_32x32x16_bf16 v[82:97], v[100:103], v[108:111], v[82:97]
	v_cvt_pk_bf16_f32 v163, v146, v147
	s_nop 0
	v_permlane32_swap_b32_e32 v148, v150
	v_permlane32_swap_b32_e32 v149, v151
	s_waitcnt lgkmcnt(0)
	v_mfma_f32_32x32x16_bf16 v[66:81], v[136:139], v[108:111], v[66:81]
	v_permlane32_swap_b32_e32 v152, v154
	v_permlane32_swap_b32_e32 v153, v155
	v_permlane32_swap_b32_e32 v156, v158
	ds_read_b128 v[100:103], v195 offset:49280
	ds_read_b128 v[136:139], v195 offset:57472
	ds_read_b64_tr_b16 v[172:173], v185 offset:0
	ds_read_b64_tr_b16 v[174:175], v185 offset:0x800
	ds_read_b64_tr_b16 v[202:203], v185 offset:0x1000
	ds_read_b64_tr_b16 v[204:205], v185 offset:0x1800
	ds_read_b64_tr_b16 v[206:207], v185 offset:0x2000
	ds_read_b64_tr_b16 v[208:209], v185 offset:0x2800
	ds_read_b64_tr_b16 v[224:225], v185 offset:0x3000
	ds_read_b64_tr_b16 v[226:227], v185 offset:0x3800
	s_waitcnt lgkmcnt(9)
	v_mfma_f32_32x32x16_bf16 v[82:97], v[100:103], v[104:107], v[82:97]
	v_permlane32_swap_b32_e32 v157, v159
	v_permlane32_swap_b32_e32 v160, v162
	v_permlane32_swap_b32_e32 v161, v163
	s_waitcnt lgkmcnt(8)
	v_mfma_f32_32x32x16_bf16 v[66:81], v[136:139], v[104:107], v[66:81]
	v_add_u32_e32 v178, s7, v166
	v_add_u32_e32 v100, 1, v178
	v_add_u32_e32 v102, 33, v178
	v_ashrrev_i32_e32 v101, 31, v100
	v_ashrrev_i32_e32 v103, 31, v102
	v_lshlrev_b64 v[140:141], 8, v[100:101]
	v_lshlrev_b64 v[142:143], 8, v[102:103]
	v_lshl_add_u64 v[100:101], v[170:171], 0, v[140:141]
	v_lshl_add_u64 v[136:137], v[170:171], 0, v[142:143]
	v_lshl_add_u64 v[140:141], v[176:177], 0, v[140:141]
	v_lshl_add_u64 v[144:145], v[176:177], 0, v[142:143]
	global_load_dwordx4 v[100:103], v[100:101], off
	s_nop 0
	global_load_dwordx4 v[136:139], v[136:137], off
	s_nop 0
	global_load_dwordx4 v[140:143], v[140:141], off
	s_nop 0
	global_load_dwordx4 v[144:147], v[144:145], off
	s_waitcnt lgkmcnt(0)
; __device__ __forceinline__ void mask_tile(f32x16& p0, f32x16& p1, int dq, unsigned W) {
;     const float NEG = -__builtin_inff();
; #pragma unroll
;     for (int r = 0; r < 16; ++r) {
;         const int c = (r & 3) + 8 * (r >> 2);
;         if ((unsigned)(dq - c) >= W) p0[r] = NEG;
;         if ((unsigned)(dq - c - 32) >= W) p1[r] = NEG;
;     }
; }
; template <int VB>
; __device__ __forceinline__ void pv_tile(f32x16* o, int vb0, bf16x8 pa0, bf16x8 pa1, bf16x8 pa2, bf16x8 pa3) {
;     ...
;     PV_D0(0); PV_D0(1); PV_D0(2); PV_D0(3);
	s_nop 0
	v_mfma_f32_32x32x16_bf16 v[50:65], v[148:151], v[172:175], v[50:65]
	ds_read_b64_tr_b16 v[172:173], v185 offset:0x200
	ds_read_b64_tr_b16 v[174:175], v185 offset:0xa00
	v_mfma_f32_32x32x16_bf16 v[50:65], v[152:155], v[202:205], v[50:65]
	ds_read_b64_tr_b16 v[202:203], v185 offset:0x1200
	ds_read_b64_tr_b16 v[204:205], v185 offset:0x1a00
	v_mfma_f32_32x32x16_bf16 v[50:65], v[156:159], v[206:209], v[50:65]
	ds_read_b64_tr_b16 v[206:207], v185 offset:0x2200
	ds_read_b64_tr_b16 v[208:209], v185 offset:0x2a00
	v_mfma_f32_32x32x16_bf16 v[50:65], v[160:163], v[224:227], v[50:65]
	ds_read_b64_tr_b16 v[224:225], v185 offset:0x3200
	ds_read_b64_tr_b16 v[226:227], v185 offset:0x3a00
	s_waitcnt lgkmcnt(0)
	v_mfma_f32_32x32x16_bf16 v[34:49], v[148:151], v[172:175], v[34:49]
	ds_read_b64_tr_b16 v[172:173], v185 offset:0x400
	ds_read_b64_tr_b16 v[174:175], v185 offset:0xc00
	v_mfma_f32_32x32x16_bf16 v[34:49], v[152:155], v[202:205], v[34:49]
	ds_read_b64_tr_b16 v[202:203], v185 offset:0x1400
	ds_read_b64_tr_b16 v[204:205], v185 offset:0x1c00
	v_mfma_f32_32x32x16_bf16 v[34:49], v[156:159], v[206:209], v[34:49]
	ds_read_b64_tr_b16 v[206:207], v185 offset:0x2400
	ds_read_b64_tr_b16 v[208:209], v185 offset:0x2c00
	v_mfma_f32_32x32x16_bf16 v[34:49], v[160:163], v[224:227], v[34:49]
	ds_read_b64_tr_b16 v[224:225], v185 offset:0x3400
	ds_read_b64_tr_b16 v[226:227], v185 offset:0x3c00
	s_waitcnt lgkmcnt(0)
	v_mfma_f32_32x32x16_bf16 v[18:33], v[148:151], v[172:175], v[18:33]
	ds_read_b64_tr_b16 v[172:173], v185 offset:0x600
	ds_read_b64_tr_b16 v[174:175], v185 offset:0xe00
	v_mfma_f32_32x32x16_bf16 v[18:33], v[152:155], v[202:205], v[18:33]
	ds_read_b64_tr_b16 v[202:203], v185 offset:0x1600
	ds_read_b64_tr_b16 v[204:205], v185 offset:0x1e00
	v_mfma_f32_32x32x16_bf16 v[18:33], v[156:159], v[206:209], v[18:33]
	ds_read_b64_tr_b16 v[206:207], v185 offset:0x2600
	ds_read_b64_tr_b16 v[208:209], v185 offset:0x2e00
	v_mfma_f32_32x32x16_bf16 v[18:33], v[160:163], v[224:227], v[18:33]
	ds_read_b64_tr_b16 v[224:225], v185 offset:0x3600
	ds_read_b64_tr_b16 v[226:227], v185 offset:0x3e00
	s_waitcnt lgkmcnt(0)
	v_mfma_f32_32x32x16_bf16 v[2:17], v[148:151], v[172:175], v[2:17]
	s_cmp_le_i32 s7, s6
	v_mfma_f32_32x32x16_bf16 v[2:17], v[152:155], v[202:205], v[2:17]
	v_mfma_f32_32x32x16_bf16 v[2:17], v[156:159], v[206:209], v[2:17]
	v_mfma_f32_32x32x16_bf16 v[2:17], v[160:163], v[224:227], v[2:17]
	s_cmp_eq_u32 s32, 0
	s_cbranch_scc1 .Lmy_pp1_a
	s_waitcnt vmcnt(0)
	ds_write_b128 v188, v[140:143] offset:32768
	ds_write_b128 v188, v[144:147] offset:40960
	s_waitcnt lgkmcnt(0)
	s_barrier
.Lmy_pp1_a:
	s_cmp_le_i32 s7, s6
	s_cbranch_scc1 .LBB0_91
	v_add_u32_e32 v148, 0x4000007b, v197
	v_cmp_gt_u32_e32 vcc, 2.0, v148
	v_add_u32_e32 v148, 0x5b, v197
	s_nop 0
	v_cndmask_b32_e32 v82, v220, v82, vcc
	v_cmp_lt_u32_e32 vcc, s33, v148
	v_add_u32_e32 v148, 0x7a, v197
	s_nop 0
	v_cndmask_b32_e32 v66, v220, v66, vcc
	v_cmp_lt_u32_e32 vcc, s33, v148
	v_add_u32_e32 v148, 0x5a, v197
	s_nop 0
	v_cndmask_b32_e32 v83, v220, v83, vcc
	v_cmp_lt_u32_e32 vcc, s33, v148
	v_add_u32_e32 v148, 0x79, v197
	s_nop 0
	v_cndmask_b32_e32 v67, v220, v67, vcc
	v_cmp_lt_u32_e32 vcc, s33, v148
	v_add_u32_e32 v148, 0x59, v197
	s_nop 0
	v_cndmask_b32_e32 v84, v220, v84, vcc
	v_cmp_lt_u32_e32 vcc, s33, v148
	v_add_u32_e32 v148, 0x78, v197
	s_nop 0
	v_cndmask_b32_e32 v68, v220, v68, vcc
	v_cmp_lt_u32_e32 vcc, s33, v148
	v_add_u32_e32 v148, 0x58, v197
	s_nop 0
	v_cndmask_b32_e32 v85, v220, v85, vcc
	v_cmp_lt_u32_e32 vcc, s33, v148
	v_add_u32_e32 v148, 0x73, v197
	s_nop 0
	v_cndmask_b32_e32 v69, v220, v69, vcc
	v_cmp_lt_u32_e32 vcc, s33, v148
	v_add_u32_e32 v148, 0x53, v197
	s_nop 0
	v_cndmask_b32_e32 v86, v220, v86, vcc
	v_cmp_lt_u32_e32 vcc, s33, v148
	v_add_u32_e32 v148, 0x72, v197
	s_nop 0
	v_cndmask_b32_e32 v70, v220, v70, vcc
	v_cmp_lt_u32_e32 vcc, s33, v148
	v_add_u32_e32 v148, 0x52, v197
	s_nop 0
	v_cndmask_b32_e32 v87, v220, v87, vcc
	v_cmp_lt_u32_e32 vcc, s33, v148
	v_add_u32_e32 v148, 0x71, v197
	s_nop 0
	v_cndmask_b32_e32 v71, v220, v71, vcc
	v_cmp_lt_u32_e32 vcc, s33, v148
	v_add_u32_e32 v148, 0x51, v197
	s_nop 0
	v_cndmask_b32_e32 v88, v220, v88, vcc
	v_cmp_lt_u32_e32 vcc, s33, v148
	v_add_u32_e32 v148, 0x70, v197
	s_nop 0
	v_cndmask_b32_e32 v72, v220, v72, vcc
	v_cmp_lt_u32_e32 vcc, s33, v148
	v_add_u32_e32 v148, 0x50, v197
	s_nop 0
	v_cndmask_b32_e32 v89, v220, v89, vcc
	v_cmp_lt_u32_e32 vcc, s33, v148
	v_add_u32_e32 v148, 0x6b, v197
	s_nop 0
	v_cndmask_b32_e32 v73, v220, v73, vcc
	v_cmp_lt_u32_e32 vcc, s33, v148
	v_add_u32_e32 v148, 0x4b, v197
	s_nop 0
	v_cndmask_b32_e32 v90, v220, v90, vcc
	v_cmp_lt_u32_e32 vcc, s33, v148
	v_add_u32_e32 v148, 0x6a, v197
	s_nop 0
	v_cndmask_b32_e32 v74, v220, v74, vcc
	v_cmp_lt_u32_e32 vcc, s33, v148
	v_add_u32_e32 v148, 0x4a, v197
	s_nop 0
	v_cndmask_b32_e32 v91, v220, v91, vcc
	v_cmp_lt_u32_e32 vcc, s33, v148
	v_add_u32_e32 v148, 0x69, v197
	s_nop 0
	v_cndmask_b32_e32 v75, v220, v75, vcc
	v_cmp_lt_u32_e32 vcc, s33, v148
	v_add_u32_e32 v148, 0x49, v197
	s_nop 0
	v_cndmask_b32_e32 v92, v220, v92, vcc
	v_cmp_lt_u32_e32 vcc, s33, v148
	v_add_u32_e32 v148, 0x68, v197
	s_nop 0
	v_cndmask_b32_e32 v76, v220, v76, vcc
	v_cmp_lt_u32_e32 vcc, s33, v148
	v_add_u32_e32 v148, 0x48, v197
	s_nop 0
	v_cndmask_b32_e32 v93, v220, v93, vcc
	v_cmp_lt_u32_e32 vcc, s33, v148
	v_add_u32_e32 v148, 0x63, v197
	s_nop 0
	v_cndmask_b32_e32 v77, v220, v77, vcc
	v_cmp_lt_u32_e32 vcc, s33, v148
	v_add_u32_e32 v148, 0x43, v197
	s_nop 0
	v_cndmask_b32_e32 v94, v220, v94, vcc
	v_cmp_lt_u32_e32 vcc, s33, v148
	v_add_u32_e32 v148, 0x62, v197
	s_nop 0
	v_cndmask_b32_e32 v78, v220, v78, vcc
	v_cmp_lt_u32_e32 vcc, s33, v148
	v_add_u32_e32 v148, 0x42, v197
	s_nop 0
	v_cndmask_b32_e32 v95, v220, v95, vcc
	v_cmp_lt_u32_e32 vcc, s33, v148
	v_add_u32_e32 v148, 0x61, v197
	s_nop 0
	v_cndmask_b32_e32 v79, v220, v79, vcc
	v_cmp_lt_u32_e32 vcc, s33, v148
	v_add_u32_e32 v148, 0x41, v197
	s_nop 0
	v_cndmask_b32_e32 v96, v220, v96, vcc
	v_cmp_lt_u32_e32 vcc, s33, v148
	v_add_u32_e32 v148, 0x60, v197
	s_nop 0
	v_cndmask_b32_e32 v80, v220, v80, vcc
	v_cmp_lt_u32_e32 vcc, s33, v148
	v_add_u32_e32 v148, 64, v197
	s_nop 0
	v_cndmask_b32_e32 v97, v220, v97, vcc
	v_cmp_lt_u32_e32 vcc, s33, v148
	s_nop 1
	v_cndmask_b32_e32 v81, v220, v81, vcc
; __device__ __forceinline__ void partialSM(f32x16& p0, f32x16& p1, float& m_reg, float& mn, float& alpha, bool rs) {
;     float pmax = p0[0]; for (int r = 1; r < 16; ++r) pmax = fmaxf(pmax, p0[r]); for (int r = 0; r < 16; ++r) pmax = fmaxf(pmax, p1[r]);
;     if (!rs) pmax = -__builtin_inff();
;     { auto rr = __builtin_amdgcn_permlane32_swap(__float_as_uint(pmax), __float_as_uint(pmax), false, false);
;       pmax = fmaxf(__uint_as_float(rr[0]), __uint_as_float(rr[1])); }
;     constexpr float C2 = 1.4426950408889634f * SCALE;
;     if (__builtin_expect(__all((pmax - m_reg) * SCALE <= THR), 1)) { mn = m_reg; alpha = 1.f; }
;     else { mn = fmaxf(m_reg, pmax); alpha = __builtin_amdgcn_exp2f((m_reg - mn) * C2); m_reg = mn; }
;     const float mnL = rs ? -mn * C2 : -__builtin_inff();
;     for (int r = 0; r < 16; ++r) p0[r] = fmaf(p0[r], C2, mnL); for (int r = 0; r < 16; ++r) p1[r] = fmaf(p1[r], C2, mnL);
;     for (int r = 0; r < 16; ++r) p0[r] = __builtin_amdgcn_exp2f(p0[r]);
; }
.LBB0_91:
	s_add_i32 s0, s3, -2
	s_lshr_b32 s8, s0, 2
	s_cmp_ge_i32 s8, s44
	s_cselect_b64 s[0:1], -1, 0
	s_lshl_b32 s8, 1, s8
	v_and_b32_e32 v148, s8, v165
	v_cmp_ne_u32_e32 vcc, 0, v148
	v_max_f32_e32 v148, v83, v83
	v_max_f32_e32 v149, v82, v82
	v_max_f32_e32 v148, v149, v148
	v_max3_f32 v148, v148, v84, v85
	v_max3_f32 v148, v148, v86, v87
	v_max3_f32 v148, v148, v88, v89
	v_max3_f32 v148, v148, v90, v91
	v_max3_f32 v148, v148, v92, v93
	v_max3_f32 v148, v148, v94, v95
	v_max3_f32 v148, v148, v96, v97
	v_max3_f32 v148, v148, v66, v67
	v_max3_f32 v148, v148, v68, v69
	v_max3_f32 v148, v148, v70, v71
	v_max3_f32 v148, v148, v72, v73
	v_max3_f32 v148, v148, v74, v75
	v_max3_f32 v148, v148, v76, v77
	v_max3_f32 v148, v148, v78, v79
	s_or_b64 s[40:41], s[0:1], vcc
	v_max3_f32 v148, v148, v80, v81
	v_cndmask_b32_e64 v148, v220, v148, s[40:41]
	v_mov_b32_e32 v149, v148
	s_nop 1
	v_permlane32_swap_b32_e32 v148, v149
	v_max_f32_e32 v149, v149, v149
	v_max_f32_e32 v148, v148, v148
	v_max_f32_e32 v148, v148, v149
	v_sub_f32_e32 v149, v148, v198
	v_mul_f32_e32 v149, 0x3db504f3, v149
	v_cmp_ge_f32_e32 vcc, s91, v149
	v_max_f32_e32 v149, v198, v198
	v_max_f32_e32 v148, v149, v148
	v_sub_f32_e32 v149, v198, v148
	v_mul_f32_e32 v149, 0x3e0293ee, v149
	v_exp_f32_e32 v149, v149
	s_cmp_eq_u64 vcc, exec
	s_cselect_b64 s[42:43], -1, 0
	s_waitcnt vmcnt(0)
	v_cndmask_b32_e64 v202, v149, 1.0, s[42:43]
	v_cmp_gt_f32_e32 vcc, 1.0, v202
	s_cmp_lg_u32 s32, 0
	s_cbranch_scc1 .Lmy_pp1_nok
	s_waitcnt vmcnt(1)
	ds_write_b128 v188, v[140:143] offset:32768
	s_waitcnt vmcnt(0)
	ds_write_b128 v188, v[144:147] offset:40960
.Lmy_pp1_nok:
	s_cbranch_vccz .LBB0_95
	s_and_saveexec_b64 s[0:1], s[38:39]
	ds_write_b32 v187, v202 offset:128
	s_or_b64 exec, exec, s[0:1]
	s_waitcnt lgkmcnt(0)
	ds_read_b128 v[150:153], v186 offset:224
	ds_read_b128 v[154:157], v186 offset:192
	ds_read_b128 v[158:161], v186 offset:160
	ds_read_b128 v[172:175], v186 offset:128
	s_waitcnt lgkmcnt(3)
	v_pk_mul_f32 v[64:65], v[64:65], v[152:153]
	s_waitcnt lgkmcnt(2)
	v_pk_mul_f32 v[60:61], v[60:61], v[156:157]
	s_waitcnt lgkmcnt(1)
	v_pk_mul_f32 v[56:57], v[56:57], v[160:161]
	s_waitcnt lgkmcnt(0)
	v_pk_mul_f32 v[52:53], v[52:53], v[174:175]
	v_pk_mul_f32 v[62:63], v[62:63], v[150:151]
	v_pk_mul_f32 v[58:59], v[58:59], v[154:155]
	v_pk_mul_f32 v[54:55], v[54:55], v[158:159]
	v_pk_mul_f32 v[50:51], v[50:51], v[172:173]
	v_pk_mul_f32 v[48:49], v[48:49], v[152:153]
	v_pk_mul_f32 v[44:45], v[44:45], v[156:157]
	v_pk_mul_f32 v[40:41], v[40:41], v[160:161]
	v_pk_mul_f32 v[36:37], v[36:37], v[174:175]
	v_pk_mul_f32 v[46:47], v[46:47], v[150:151]
	v_pk_mul_f32 v[42:43], v[42:43], v[154:155]
	v_pk_mul_f32 v[38:39], v[38:39], v[158:159]
	v_pk_mul_f32 v[34:35], v[34:35], v[172:173]
	v_pk_mul_f32 v[32:33], v[32:33], v[152:153]
	v_pk_mul_f32 v[28:29], v[28:29], v[156:157]
	v_pk_mul_f32 v[24:25], v[24:25], v[160:161]
	v_pk_mul_f32 v[20:21], v[20:21], v[174:175]
	v_pk_mul_f32 v[30:31], v[30:31], v[150:151]
	v_pk_mul_f32 v[26:27], v[26:27], v[154:155]
	v_pk_mul_f32 v[22:23], v[22:23], v[158:159]
	v_pk_mul_f32 v[18:19], v[18:19], v[172:173]
	v_pk_mul_f32 v[16:17], v[16:17], v[152:153]
	v_pk_mul_f32 v[12:13], v[12:13], v[156:157]
	v_pk_mul_f32 v[8:9], v[8:9], v[160:161]
	v_pk_mul_f32 v[4:5], v[4:5], v[174:175]
	v_pk_mul_f32 v[14:15], v[14:15], v[150:151]
	v_pk_mul_f32 v[10:11], v[10:11], v[154:155]
	v_pk_mul_f32 v[6:7], v[6:7], v[158:159]
	v_pk_mul_f32 v[2:3], v[2:3], v[172:173]
.LBB0_95:
	v_cndmask_b32_e64 v179, v148, v198, s[42:43]
	v_mul_f32_e32 v148, 0xbe0293ee, v179
	v_cndmask_b32_e64 v180, v220, v148, s[40:41]
	v_fmamk_f32 v82, v82, 0x3e0293ee, v180
	v_fmamk_f32 v83, v83, 0x3e0293ee, v180
	v_fmamk_f32 v84, v84, 0x3e0293ee, v180
	v_fmamk_f32 v85, v85, 0x3e0293ee, v180
	v_fmamk_f32 v86, v86, 0x3e0293ee, v180
	v_fmamk_f32 v87, v87, 0x3e0293ee, v180
	v_fmamk_f32 v88, v88, 0x3e0293ee, v180
	v_fmamk_f32 v89, v89, 0x3e0293ee, v180
	v_fmamk_f32 v90, v90, 0x3e0293ee, v180
	v_fmamk_f32 v91, v91, 0x3e0293ee, v180
	v_fmamk_f32 v92, v92, 0x3e0293ee, v180
	v_fmamk_f32 v93, v93, 0x3e0293ee, v180
	v_fmamk_f32 v94, v94, 0x3e0293ee, v180
	v_fmamk_f32 v95, v95, 0x3e0293ee, v180
	v_fmamk_f32 v96, v96, 0x3e0293ee, v180
	v_fmamk_f32 v97, v97, 0x3e0293ee, v180
	v_exp_f32_e32 v148, v82
	v_exp_f32_e32 v163, v83
	v_exp_f32_e32 v149, v84
	v_exp_f32_e32 v162, v85
	v_exp_f32_e32 v150, v86
	v_exp_f32_e32 v161, v87
	v_exp_f32_e32 v151, v88
	v_exp_f32_e32 v160, v89
	v_exp_f32_e32 v152, v90
	v_exp_f32_e32 v159, v91
	v_exp_f32_e32 v153, v92
	v_exp_f32_e32 v158, v93
	v_exp_f32_e32 v154, v94
	v_exp_f32_e32 v157, v95
	v_exp_f32_e32 v155, v96
	v_exp_f32_e32 v156, v97
	v_fmamk_f32 v203, v73, 0x3e0293ee, v180
	v_fmamk_f32 v204, v74, 0x3e0293ee, v180
	v_fmamk_f32 v208, v66, 0x3e0293ee, v180
	v_fmamk_f32 v209, v67, 0x3e0293ee, v180
	v_fmamk_f32 v223, v68, 0x3e0293ee, v180
	v_fmamk_f32 v224, v69, 0x3e0293ee, v180
	v_fmamk_f32 v225, v70, 0x3e0293ee, v180
	v_fmamk_f32 v198, v71, 0x3e0293ee, v180
	v_fmamk_f32 v201, v72, 0x3e0293ee, v180
	v_fmamk_f32 v205, v75, 0x3e0293ee, v180
	v_fmamk_f32 v206, v76, 0x3e0293ee, v180
	v_fmamk_f32 v207, v77, 0x3e0293ee, v180
	v_fmamk_f32 v181, v78, 0x3e0293ee, v180
	v_fmamk_f32 v226, v79, 0x3e0293ee, v180
	v_fmamk_f32 v227, v80, 0x3e0293ee, v180
	v_fmac_f32_e32 v180, 0x3e0293ee, v81
	s_cmp_lg_u32 s32, 0
	s_cbranch_scc1 .Lmy_pp1_nob
	s_waitcnt lgkmcnt(0)
	s_barrier
; __device__ __forceinline__ void finishSM(f32x16& p0, f32x16& p1, float alpha, float& l_reg, bf16x8& pa0, bf16x8& pa1, bf16x8& pa2, bf16x8& pa3) {
;     for (int r = 0; r < 16; ++r) p1[r] = __builtin_amdgcn_exp2f(p1[r]);
;     float ps = 0; for (int r = 0; r < 16; ++r) ps += p0[r]; for (int r = 0; r < 16; ++r) ps += p1[r];
;     { auto rr = __builtin_amdgcn_permlane32_swap(__float_as_uint(ps), __float_as_uint(ps), false, false);
;       ps = __uint_as_float(rr[0]) + __uint_as_float(rr[1]); }
;     l_reg = l_reg * alpha + ps;
;     ...
;     PK4(p0, 0, pa0); PK4(p0, 8, pa1); PK4(p1, 0, pa2); PK4(p1, 8, pa3);
;     ...
; }
; template <int KB>
; __device__ __forceinline__ void qkt(f32x16& p0, f32x16& p1, const char* K_lds, int r32, int hi, const bf16x8* qr) {
;     p0 = f32x16{}; p1 = f32x16{};
;     const char* kb[4];
; #pragma unroll
;     for (int dd = 0; dd < 4; ++dd) kb[dd] = K_lds + KB * SHM_K + KSWZ(r32, (dd * 16 + hi * 8) * 2);
; #pragma unroll
;     for (int d0 = 0; d0 < 8; ++d0) { const char* a = kb[d0 & 3] + (d0 >> 2) * 128;
;         bf16x8 b0 = *reinterpret_cast<const bf16x8*>(a);
;         bf16x8 b1 = *reinterpret_cast<const bf16x8*>(a + 32 * 256);
;         p0 = __builtin_amdgcn_mfma_f32_32x32x16_bf16(b0, qr[d0], p0, 0, 0, 0);
;         p1 = __builtin_amdgcn_mfma_f32_32x32x16_bf16(b1, qr[d0], p1, 0, 0, 0); }
.Lmy_pp1_nob:
	s_waitcnt vmcnt(0)
	ds_write_b128 v191, v[100:103]
	ds_write_b128 v192, v[136:139]
	ds_read_b128 v[66:69], v169 offset:32768
	ds_read_b128 v[70:73], v169 offset:40960
	ds_read_b128 v[172:175], v193 offset:32768
	ds_read_b128 v[228:231], v193 offset:40960
	v_exp_f32_e32 v198, v198
	v_exp_f32_e32 v201, v201
	v_exp_f32_e32 v214, v204
	v_exp_f32_e32 v205, v205
	v_exp_f32_e32 v206, v206
	v_exp_f32_e32 v207, v207
	v_exp_f32_e32 v181, v181
	v_exp_f32_e32 v215, v226
	v_exp_f32_e32 v216, v227
	v_exp_f32_e32 v180, v180
	v_exp_f32_e32 v218, v209
	v_exp_f32_e32 v209, v203
	v_add_f32_e32 v203, 0, v148
	v_add_f32_e32 v203, v163, v203
	v_add_f32_e32 v203, v149, v203
	v_add_f32_e32 v203, v162, v203
	v_add_f32_e32 v203, v150, v203
	v_add_f32_e32 v203, v161, v203
	v_add_f32_e32 v203, v151, v203
	v_add_f32_e32 v203, v160, v203
	s_waitcnt lgkmcnt(3)
	v_mfma_f32_32x32x16_bf16 v[82:97], v[66:69], v[132:135], 0
	v_add_f32_e32 v203, v152, v203
	v_add_f32_e32 v203, v159, v203
	v_add_f32_e32 v203, v153, v203
	v_add_f32_e32 v203, v158, v203
	s_waitcnt lgkmcnt(2)
	v_mfma_f32_32x32x16_bf16 v[66:81], v[70:73], v[132:135], 0
	v_exp_f32_e32 v217, v208
	v_add_f32_e32 v203, v154, v203
	v_add_f32_e32 v203, v157, v203
	v_exp_f32_e32 v219, v223
	s_waitcnt lgkmcnt(1)
	v_mfma_f32_32x32x16_bf16 v[82:97], v[172:175], v[128:131], v[82:97]
	v_add_f32_e32 v203, v155, v203
	v_exp_f32_e32 v222, v224
	v_add_f32_e32 v203, v156, v203
	v_exp_f32_e32 v208, v225
	s_waitcnt lgkmcnt(0)
	v_mfma_f32_32x32x16_bf16 v[66:81], v[228:231], v[128:131], v[66:81]
	v_add_f32_e32 v203, v217, v203
	v_add_f32_e32 v203, v218, v203
	v_add_f32_e32 v203, v219, v203
	v_add_f32_e32 v203, v222, v203
	ds_read_b128 v[172:175], v194 offset:32768
	ds_read_b128 v[228:231], v194 offset:40960
	s_waitcnt lgkmcnt(1)
	v_mfma_f32_32x32x16_bf16 v[82:97], v[172:175], v[124:127], v[82:97]
	v_add_f32_e32 v203, v208, v203
	v_add_f32_e32 v203, v198, v203
	v_add_f32_e32 v203, v201, v203
	v_add_f32_e32 v203, v209, v203
	s_waitcnt lgkmcnt(0)
	v_mfma_f32_32x32x16_bf16 v[66:81], v[228:231], v[124:127], v[66:81]
	v_add_f32_e32 v203, v214, v203
	v_add_f32_e32 v203, v205, v203
	v_add_f32_e32 v203, v206, v203
	v_add_f32_e32 v203, v207, v203
	ds_read_b128 v[172:175], v195 offset:32768
	ds_read_b128 v[228:231], v195 offset:40960
	s_waitcnt lgkmcnt(1)
	v_mfma_f32_32x32x16_bf16 v[82:97], v[172:175], v[120:123], v[82:97]
	v_add_f32_e32 v203, v181, v203
	v_add_f32_e32 v203, v215, v203
	v_add_f32_e32 v203, v216, v203
	v_add_f32_e32 v203, v180, v203
	s_waitcnt lgkmcnt(0)
	v_mfma_f32_32x32x16_bf16 v[66:81], v[228:231], v[120:123], v[66:81]
	v_mov_b32_e32 v204, v203
	v_cvt_pk_bf16_f32 v148, v148, v163
	v_cvt_pk_bf16_f32 v149, v149, v162
	v_cvt_pk_bf16_f32 v150, v150, v161
	ds_read_b128 v[172:175], v169 offset:32896
	ds_read_b128 v[228:231], v169 offset:41088
	s_waitcnt lgkmcnt(1)
	v_mfma_f32_32x32x16_bf16 v[82:97], v[172:175], v[116:119], v[82:97]
	v_cvt_pk_bf16_f32 v151, v151, v160
	v_cvt_pk_bf16_f32 v152, v152, v159
	v_cvt_pk_bf16_f32 v153, v153, v158
	v_cvt_pk_bf16_f32 v154, v154, v157
	s_waitcnt lgkmcnt(0)
	v_mfma_f32_32x32x16_bf16 v[66:81], v[228:231], v[116:119], v[66:81]
	v_cvt_pk_bf16_f32 v155, v155, v156
	v_cvt_pk_bf16_f32 v156, v217, v218
	v_cvt_pk_bf16_f32 v157, v219, v222
	ds_read_b128 v[172:175], v193 offset:32896
	ds_read_b128 v[228:231], v193 offset:41088
	s_waitcnt lgkmcnt(1)
	v_mfma_f32_32x32x16_bf16 v[82:97], v[172:175], v[112:115], v[82:97]
	v_cvt_pk_bf16_f32 v158, v208, v198
	v_cvt_pk_bf16_f32 v159, v201, v209
	v_cvt_pk_bf16_f32 v160, v214, v205
	s_waitcnt lgkmcnt(0)
	v_mfma_f32_32x32x16_bf16 v[66:81], v[228:231], v[112:115], v[66:81]
	v_cvt_pk_bf16_f32 v161, v206, v207
	v_cvt_pk_bf16_f32 v162, v181, v215
	v_cvt_pk_bf16_f32 v163, v216, v180
	ds_read_b128 v[172:175], v194 offset:32896
	ds_read_b128 v[228:231], v194 offset:41088
	s_waitcnt lgkmcnt(1)
	v_mfma_f32_32x32x16_bf16 v[82:97], v[172:175], v[108:111], v[82:97]
	s_nop 1
	v_permlane32_swap_b32_e32 v203, v204
	v_permlane32_swap_b32_e32 v148, v150
	v_permlane32_swap_b32_e32 v149, v151
	s_waitcnt lgkmcnt(0)
	v_mfma_f32_32x32x16_bf16 v[66:81], v[228:231], v[108:111], v[66:81]
	v_permlane32_swap_b32_e32 v152, v154
	v_permlane32_swap_b32_e32 v153, v155
	v_permlane32_swap_b32_e32 v156, v158
	ds_read_b128 v[172:175], v195 offset:32896
	ds_read_b128 v[228:231], v195 offset:41088
	ds_read_b64_tr_b16 v[206:207], v185 offset:0x5000
	ds_read_b64_tr_b16 v[208:209], v185 offset:0x5800
	ds_read_b64_tr_b16 v[224:225], v185 offset:0x6000
	ds_read_b64_tr_b16 v[226:227], v185 offset:0x6800
	s_waitcnt lgkmcnt(5)
	v_mfma_f32_32x32x16_bf16 v[82:97], v[172:175], v[104:107], v[82:97]
	v_permlane32_swap_b32_e32 v157, v159
	v_permlane32_swap_b32_e32 v160, v162
	v_permlane32_swap_b32_e32 v161, v163
	s_waitcnt lgkmcnt(4)
	v_mfma_f32_32x32x16_bf16 v[66:81], v[228:231], v[104:107], v[66:81]
	ds_read_b64_tr_b16 v[172:173], v185 offset:0x4000
	ds_read_b64_tr_b16 v[174:175], v185 offset:0x4800
	ds_read_b64_tr_b16 v[228:229], v185 offset:0x7000
	ds_read_b64_tr_b16 v[230:231], v185 offset:0x7800
	s_cmp_lt_u32 s3, s2
	s_cselect_b64 s[22:23], -1, 0
	s_cmp_ge_u32 s3, s2
	s_cbranch_scc1 .LBB0_97
	v_add_u32_e32 v242, 0x41, v178
	v_add_u32_e32 v246, 0x61, v178
	v_ashrrev_i32_e32 v243, 31, v242
	v_ashrrev_i32_e32 v247, 31, v246
	v_lshlrev_b64 v[140:141], 8, v[242:243]
	v_lshlrev_b64 v[142:143], 8, v[246:247]
	v_lshl_add_u64 v[242:243], v[170:171], 0, v[140:141]
	v_lshl_add_u64 v[246:247], v[170:171], 0, v[142:143]
	v_lshl_add_u64 v[140:141], v[176:177], 0, v[140:141]
	v_lshl_add_u64 v[144:145], v[176:177], 0, v[142:143]
	global_load_dwordx4 v[242:245], v[242:243], off
	s_nop 0
	global_load_dwordx4 v[246:249], v[246:247], off
	s_nop 0
	global_load_dwordx4 v[140:143], v[140:141], off
	s_nop 0
	global_load_dwordx4 v[144:147], v[144:145], off
	s_mov_b32 s100, 1
; template <int VB>
; __device__ __forceinline__ void pv_tile(f32x16* o, int vb0, bf16x8 pa0, bf16x8 pa1, bf16x8 pa2, bf16x8 pa3) {
;     ...
;     PV_D0(0); PV_D0(1); PV_D0(2); PV_D0(3);
.LBB0_97:
	s_waitcnt lgkmcnt(0)
	s_nop 0
	v_mfma_f32_32x32x16_bf16 v[50:65], v[148:151], v[172:175], v[50:65]
	ds_read_b64_tr_b16 v[172:173], v185 offset:0x4200
	ds_read_b64_tr_b16 v[174:175], v185 offset:0x4a00
	v_mfma_f32_32x32x16_bf16 v[50:65], v[152:155], v[206:209], v[50:65]
	ds_read_b64_tr_b16 v[206:207], v185 offset:0x5200
	ds_read_b64_tr_b16 v[208:209], v185 offset:0x5a00
	v_mfma_f32_32x32x16_bf16 v[50:65], v[156:159], v[224:227], v[50:65]
	ds_read_b64_tr_b16 v[224:225], v185 offset:0x6200
	ds_read_b64_tr_b16 v[226:227], v185 offset:0x6a00
	v_mfma_f32_32x32x16_bf16 v[50:65], v[160:163], v[228:231], v[50:65]
	ds_read_b64_tr_b16 v[228:229], v185 offset:0x7200
	ds_read_b64_tr_b16 v[230:231], v185 offset:0x7a00
	s_waitcnt lgkmcnt(0)
	v_mfma_f32_32x32x16_bf16 v[34:49], v[148:151], v[172:175], v[34:49]
	ds_read_b64_tr_b16 v[172:173], v185 offset:0x4400
	ds_read_b64_tr_b16 v[174:175], v185 offset:0x4c00
	v_mfma_f32_32x32x16_bf16 v[34:49], v[152:155], v[206:209], v[34:49]
	ds_read_b64_tr_b16 v[206:207], v185 offset:0x5400
	ds_read_b64_tr_b16 v[208:209], v185 offset:0x5c00
	v_mfma_f32_32x32x16_bf16 v[34:49], v[156:159], v[224:227], v[34:49]
	ds_read_b64_tr_b16 v[224:225], v185 offset:0x6400
	ds_read_b64_tr_b16 v[226:227], v185 offset:0x6c00
	v_mfma_f32_32x32x16_bf16 v[34:49], v[160:163], v[228:231], v[34:49]
	ds_read_b64_tr_b16 v[228:229], v185 offset:0x7400
	ds_read_b64_tr_b16 v[230:231], v185 offset:0x7c00
	s_waitcnt lgkmcnt(0)
	v_mfma_f32_32x32x16_bf16 v[18:33], v[148:151], v[172:175], v[18:33]
	ds_read_b64_tr_b16 v[172:173], v185 offset:0x4600
	ds_read_b64_tr_b16 v[174:175], v185 offset:0x4e00
	v_mfma_f32_32x32x16_bf16 v[18:33], v[152:155], v[206:209], v[18:33]
	ds_read_b64_tr_b16 v[206:207], v185 offset:0x5600
	ds_read_b64_tr_b16 v[208:209], v185 offset:0x5e00
	v_mfma_f32_32x32x16_bf16 v[18:33], v[156:159], v[224:227], v[18:33]
	ds_read_b64_tr_b16 v[224:225], v185 offset:0x6600
	ds_read_b64_tr_b16 v[226:227], v185 offset:0x6e00
	v_mfma_f32_32x32x16_bf16 v[18:33], v[160:163], v[228:231], v[18:33]
	ds_read_b64_tr_b16 v[228:229], v185 offset:0x7600
	ds_read_b64_tr_b16 v[230:231], v185 offset:0x7e00
	s_waitcnt lgkmcnt(0)
	v_mfma_f32_32x32x16_bf16 v[2:17], v[148:151], v[172:175], v[2:17]
	s_add_i32 s0, s7, 64
	s_cmp_le_i32 s0, s6
	v_mfma_f32_32x32x16_bf16 v[2:17], v[152:155], v[206:209], v[2:17]
	v_mfma_f32_32x32x16_bf16 v[2:17], v[156:159], v[224:227], v[2:17]
	v_mfma_f32_32x32x16_bf16 v[2:17], v[160:163], v[228:231], v[2:17]
	s_cmp_eq_u32 s32, 0
	s_cbranch_scc1 .Lmy_pp2_a
	s_cmp_eq_u64 s[22:23], 0
	s_cbranch_scc1 .Lmy_pp2_nok
	s_waitcnt vmcnt(0)
	ds_write_b128 v188, v[140:143] offset:49152
	ds_write_b128 v188, v[144:147] offset:57344
.Lmy_pp2_nok:
	s_waitcnt lgkmcnt(0)
	s_barrier
; __device__ __forceinline__ void mask_tile(f32x16& p0, f32x16& p1, int dq, unsigned W) {
;     const float NEG = -__builtin_inff();
; #pragma unroll
;     for (int r = 0; r < 16; ++r) {
;         const int c = (r & 3) + 8 * (r >> 2);
;         if ((unsigned)(dq - c) >= W) p0[r] = NEG;
;         if ((unsigned)(dq - c - 32) >= W) p1[r] = NEG;
;     }
; }
; __device__ __forceinline__ void partialSM(f32x16& p0, f32x16& p1, float& m_reg, float& mn, float& alpha, bool rs) {
;     float pmax = p0[0]; for (int r = 1; r < 16; ++r) pmax = fmaxf(pmax, p0[r]); for (int r = 0; r < 16; ++r) pmax = fmaxf(pmax, p1[r]);
;     if (!rs) pmax = -__builtin_inff();
;     { auto rr = __builtin_amdgcn_permlane32_swap(__float_as_uint(pmax), __float_as_uint(pmax), false, false);
;       pmax = fmaxf(__uint_as_float(rr[0]), __uint_as_float(rr[1])); }
;     constexpr float C2 = 1.4426950408889634f * SCALE;
;     if (__builtin_expect(__all((pmax - m_reg) * SCALE <= THR), 1)) { mn = m_reg; alpha = 1.f; }
;     else { mn = fmaxf(m_reg, pmax); alpha = __builtin_amdgcn_exp2f((m_reg - mn) * C2); m_reg = mn; }
;     const float mnL = rs ? -mn * C2 : -__builtin_inff();
;     for (int r = 0; r < 16; ++r) p0[r] = fmaf(p0[r], C2, mnL); for (int r = 0; r < 16; ++r) p1[r] = fmaf(p1[r], C2, mnL);
;     for (int r = 0; r < 16; ++r) p0[r] = __builtin_amdgcn_exp2f(p0[r]);
; }
.Lmy_pp2_a:
	s_cmp_le_i32 s0, s6
	s_cbranch_scc1 .LBB0_99
	v_add_u32_e32 v148, 0x4000003b, v197
	v_cmp_gt_u32_e32 vcc, 2.0, v148
	v_add_u32_e32 v148, 27, v197
	s_nop 0
	v_cndmask_b32_e32 v82, v220, v82, vcc
	v_cmp_lt_u32_e32 vcc, s33, v148
	v_add_u32_e32 v148, 58, v197
	s_nop 0
	v_cndmask_b32_e32 v66, v220, v66, vcc
	v_cmp_lt_u32_e32 vcc, s33, v148
	v_add_u32_e32 v148, 26, v197
	s_nop 0
	v_cndmask_b32_e32 v83, v220, v83, vcc
	v_cmp_lt_u32_e32 vcc, s33, v148
	v_add_u32_e32 v148, 57, v197
	s_nop 0
	v_cndmask_b32_e32 v67, v220, v67, vcc
	v_cmp_lt_u32_e32 vcc, s33, v148
	v_add_u32_e32 v148, 25, v197
	s_nop 0
	v_cndmask_b32_e32 v84, v220, v84, vcc
	v_cmp_lt_u32_e32 vcc, s33, v148
	v_add_u32_e32 v148, 56, v197
	s_nop 0
	v_cndmask_b32_e32 v68, v220, v68, vcc
	v_cmp_lt_u32_e32 vcc, s33, v148
	v_add_u32_e32 v148, 24, v197
	s_nop 0
	v_cndmask_b32_e32 v85, v220, v85, vcc
	v_cmp_lt_u32_e32 vcc, s33, v148
	v_add_u32_e32 v148, 51, v197
	s_nop 0
	v_cndmask_b32_e32 v69, v220, v69, vcc
	v_cmp_lt_u32_e32 vcc, s33, v148
	v_add_u32_e32 v148, 19, v197
	s_nop 0
	v_cndmask_b32_e32 v86, v220, v86, vcc
	v_cmp_lt_u32_e32 vcc, s33, v148
	v_add_u32_e32 v148, 50, v197
	s_nop 0
	v_cndmask_b32_e32 v70, v220, v70, vcc
	v_cmp_lt_u32_e32 vcc, s33, v148
	v_add_u32_e32 v148, 18, v197
	s_nop 0
	v_cndmask_b32_e32 v87, v220, v87, vcc
	v_cmp_lt_u32_e32 vcc, s33, v148
	v_add_u32_e32 v148, 49, v197
	s_nop 0
	v_cndmask_b32_e32 v71, v220, v71, vcc
	v_cmp_lt_u32_e32 vcc, s33, v148
	v_add_u32_e32 v148, 17, v197
	s_nop 0
	v_cndmask_b32_e32 v88, v220, v88, vcc
	v_cmp_lt_u32_e32 vcc, s33, v148
	v_add_u32_e32 v148, 48, v197
	s_nop 0
	v_cndmask_b32_e32 v72, v220, v72, vcc
	v_cmp_lt_u32_e32 vcc, s33, v148
	v_add_u32_e32 v148, 16, v197
	s_nop 0
	v_cndmask_b32_e32 v89, v220, v89, vcc
	v_cmp_lt_u32_e32 vcc, s33, v148
	v_add_u32_e32 v148, 43, v197
	s_nop 0
	v_cndmask_b32_e32 v73, v220, v73, vcc
	v_cmp_lt_u32_e32 vcc, s33, v148
	v_add_u32_e32 v148, 11, v197
	s_nop 0
	v_cndmask_b32_e32 v90, v220, v90, vcc
	v_cmp_lt_u32_e32 vcc, s33, v148
	v_add_u32_e32 v148, 42, v197
	s_nop 0
	v_cndmask_b32_e32 v74, v220, v74, vcc
	v_cmp_lt_u32_e32 vcc, s33, v148
	v_add_u32_e32 v148, 10, v197
	s_nop 0
	v_cndmask_b32_e32 v91, v220, v91, vcc
	v_cmp_lt_u32_e32 vcc, s33, v148
	v_add_u32_e32 v148, 41, v197
	s_nop 0
	v_cndmask_b32_e32 v75, v220, v75, vcc
	v_cmp_lt_u32_e32 vcc, s33, v148
	v_add_u32_e32 v148, 9, v197
	s_nop 0
	v_cndmask_b32_e32 v92, v220, v92, vcc
	v_cmp_lt_u32_e32 vcc, s33, v148
	v_add_u32_e32 v148, 40, v197
	s_nop 0
	v_cndmask_b32_e32 v76, v220, v76, vcc
	v_cmp_lt_u32_e32 vcc, s33, v148
	v_add_u32_e32 v148, 8, v197
	s_nop 0
	v_cndmask_b32_e32 v93, v220, v93, vcc
	v_cmp_lt_u32_e32 vcc, s33, v148
	v_add_u32_e32 v148, 35, v197
	s_nop 0
	v_cndmask_b32_e32 v77, v220, v77, vcc
	v_cmp_lt_u32_e32 vcc, s33, v148
	v_add_u32_e32 v148, 3, v197
	s_nop 0
	v_cndmask_b32_e32 v94, v220, v94, vcc
	v_cmp_lt_u32_e32 vcc, s33, v148
	v_add_u32_e32 v148, 34, v197
	s_nop 0
	v_cndmask_b32_e32 v78, v220, v78, vcc
	v_cmp_lt_u32_e32 vcc, s33, v148
	v_add_u32_e32 v148, 2, v197
	s_nop 0
	v_cndmask_b32_e32 v95, v220, v95, vcc
	v_cmp_lt_u32_e32 vcc, s33, v148
	v_add_u32_e32 v148, 33, v197
	s_nop 0
	v_cndmask_b32_e32 v79, v220, v79, vcc
	v_cmp_lt_u32_e32 vcc, s33, v148
	v_add_u32_e32 v148, 1, v197
	s_nop 0
	v_cndmask_b32_e32 v96, v220, v96, vcc
	v_cmp_lt_u32_e32 vcc, s33, v148
	v_add_u32_e32 v148, 32, v197
	s_nop 0
	v_cndmask_b32_e32 v80, v220, v80, vcc
	v_cmp_lt_u32_e32 vcc, s33, v148
	s_nop 1
	v_cndmask_b32_e32 v97, v220, v97, vcc
	v_cmp_lt_u32_e32 vcc, s33, v197
	s_nop 1
	v_cndmask_b32_e32 v81, v220, v81, vcc
.LBB0_99:
	s_add_i32 s0, s3, -1
	s_lshr_b32 s8, s0, 2
	s_cmp_ge_i32 s8, s44
	s_cselect_b64 s[0:1], -1, 0
	s_lshl_b32 s8, 1, s8
	v_and_b32_e32 v148, s8, v165
	v_cmp_ne_u32_e32 vcc, 0, v148
	v_max_f32_e32 v148, v83, v83
	v_max_f32_e32 v149, v82, v82
	v_max_f32_e32 v148, v149, v148
	v_max3_f32 v148, v148, v84, v85
	v_max3_f32 v148, v148, v86, v87
	v_max3_f32 v148, v148, v88, v89
	v_max3_f32 v148, v148, v90, v91
	v_max3_f32 v148, v148, v92, v93
	v_max3_f32 v148, v148, v94, v95
	v_max3_f32 v148, v148, v96, v97
	v_max3_f32 v148, v148, v66, v67
	v_max3_f32 v148, v148, v68, v69
	v_max3_f32 v148, v148, v70, v71
	v_max3_f32 v148, v148, v72, v73
	v_max3_f32 v148, v148, v74, v75
	v_max3_f32 v148, v148, v76, v77
	v_max3_f32 v148, v148, v78, v79
	v_max3_f32 v148, v148, v80, v81
	s_or_b64 s[40:41], s[0:1], vcc
	v_cndmask_b32_e64 v148, v220, v148, s[40:41]
	v_mov_b32_e32 v149, v148
	s_nop 1
	v_permlane32_swap_b32_e32 v148, v149
	v_max_f32_e32 v149, v149, v149
	v_max_f32_e32 v148, v148, v148
	v_max_f32_e32 v148, v148, v149
	v_sub_f32_e32 v149, v148, v179
	v_mul_f32_e32 v149, 0x3db504f3, v149
	v_cmp_ge_f32_e32 vcc, s91, v149
	s_cmp_eq_u64 vcc, exec
	s_cselect_b64 s[42:43], -1, 0
	s_andn2_b64 vcc, exec, s[22:23]
	s_cbranch_vccnz .LBB0_101
	s_waitcnt vmcnt(0)
	s_cmp_lg_u32 s32, 0
	s_cbranch_scc1 .LBB0_101
	s_waitcnt vmcnt(1)
	ds_write_b128 v188, v[140:143] offset:49152
	s_waitcnt vmcnt(0)
	ds_write_b128 v188, v[144:147] offset:57344

; __device__ __forceinline__ void partialSM(f32x16& p0, f32x16& p1, float& m_reg, float& mn, float& alpha, bool rs) {
;     ...
;     else { mn = fmaxf(m_reg, pmax); alpha = __builtin_amdgcn_exp2f((m_reg - mn) * C2); m_reg = mn; }
;     const float mnL = rs ? -mn * C2 : -__builtin_inff();
;     for (int r = 0; r < 16; ++r) p0[r] = fmaf(p0[r], C2, mnL); for (int r = 0; r < 16; ++r) p1[r] = fmaf(p1[r], C2, mnL);
;     for (int r = 0; r < 16; ++r) p0[r] = __builtin_amdgcn_exp2f(p0[r]);
; __device__ __forceinline__ void moba_block(const BlockRef& cur, const BlockRef& nxt, char* lds, Seam& S) {
;     ...
;     for (int t = 1; t + 1 < NT; t += 2) {
;         HALF_STEP(pB0, pB1, mnB, alB, pA0, pA1, alA, t, 1, 0, 0);
;         HALF_STEP(pA0, pA1, mnA, alA, pB0, pB1, alB, t + 1, 0, 1, 1);
;     }
.LBB0_105:
	v_cndmask_b32_e64 v198, v100, v179, s[42:43]
	v_mul_f32_e32 v100, 0xbe0293ee, v198
	v_cndmask_b32_e64 v100, v220, v100, s[40:41]
	v_mov_b32_e32 v101, v100
	v_fmamk_f32 v82, v82, 0x3e0293ee, v100
	v_fmamk_f32 v83, v83, 0x3e0293ee, v100
	v_fmamk_f32 v84, v84, 0x3e0293ee, v100
	v_fmamk_f32 v85, v85, 0x3e0293ee, v100
	v_fmamk_f32 v86, v86, 0x3e0293ee, v100
	v_fmamk_f32 v87, v87, 0x3e0293ee, v100
	v_fmamk_f32 v88, v88, 0x3e0293ee, v100
	v_fmamk_f32 v89, v89, 0x3e0293ee, v100
	v_fmamk_f32 v90, v90, 0x3e0293ee, v100
	v_fmamk_f32 v91, v91, 0x3e0293ee, v100
	v_fmamk_f32 v92, v92, 0x3e0293ee, v100
	v_fmamk_f32 v93, v93, 0x3e0293ee, v100
	v_fmamk_f32 v94, v94, 0x3e0293ee, v100
	v_fmamk_f32 v95, v95, 0x3e0293ee, v100
	v_fmamk_f32 v96, v96, 0x3e0293ee, v100
	v_fmac_f32_e32 v101, 0x3e0293ee, v97
	v_exp_f32_e32 v231, v82
	v_exp_f32_e32 v233, v83
	v_exp_f32_e32 v229, v84
	v_exp_f32_e32 v232, v85
	v_exp_f32_e32 v228, v86
	v_exp_f32_e32 v230, v87
	v_exp_f32_e32 v226, v88
	v_exp_f32_e32 v227, v89
	v_exp_f32_e32 v223, v90
	v_exp_f32_e32 v225, v91
	v_exp_f32_e32 v209, v92
	v_exp_f32_e32 v224, v93
	v_exp_f32_e32 v206, v94
	v_exp_f32_e32 v208, v95
	v_exp_f32_e32 v205, v96
	v_exp_f32_e32 v207, v101
	v_pk_fma_f32 v[178:179], v[66:67], s[20:21], v[100:101] op_sel_hi:[1,0,0]
	v_add_f32_e32 v66, v199, v200
	v_fmac_f32_e32 v66, v196, v189
	v_add_f32_e32 v189, v203, v204
	s_add_i32 s0, s3, 2
	s_add_i32 s1, s3, 1
	s_addk_i32 s7, 0x80
	v_pk_fma_f32 v[162:163], v[68:69], s[20:21], v[100:101] op_sel_hi:[1,0,0]
	v_pk_fma_f32 v[158:159], v[70:71], s[20:21], v[100:101] op_sel_hi:[1,0,0]
	v_pk_fma_f32 v[156:157], v[72:73], s[20:21], v[100:101] op_sel_hi:[1,0,0]
	v_pk_fma_f32 v[152:153], v[74:75], s[20:21], v[100:101] op_sel_hi:[1,0,0]
	v_pk_fma_f32 v[180:181], v[76:77], s[20:21], v[100:101] op_sel_hi:[1,0,0]
	v_pk_fma_f32 v[160:161], v[78:79], s[20:21], v[100:101] op_sel_hi:[1,0,0]
	v_pk_fma_f32 v[154:155], v[80:81], s[20:21], v[100:101] op_sel_hi:[1,0,0]
	v_fmac_f32_e32 v189, v66, v202
	s_cmp_lt_u32 s1, s2
	v_add_u32_e32 v197, 0xffffff80, v197
	s_cmp_lg_u32 s32, 0
	s_cbranch_scc1 .Lmy_pp2_nob
	s_waitcnt lgkmcnt(0)
	s_barrier
.Lmy_pp2_nob:
	s_cmp_lt_u32 s1, s2
	s_cbranch_scc0 .LBB0_107
	s_mov_b32 s3, s0
	v_mov_b32_e32 v196, v201
	s_branch .LBB0_89
